# tail of FFN gate/up phase also takes the sample-group conv-state shift; tail streaming code issues all loads of a part first
# speedup vs baseline: 1.0481x; 1.0001x over previous
; __device__ __forceinline__ void p0_prologue(const Params& p, unsigned char* lds) {
;     ...
;     { float* scs = p.out + O_SCS; const float* sc = p.in[I_SC]; constexpr int RW = (CW - 1 - DS) * MIXB / 4; constexpr size_t NCP = (size_t)DB * RW;
;       for (size_t i0 = gt; i0 < NCP; i0 += 4 * NT) { f32x4 v[4]; size_t d[4];
; #pragma unroll
;           for (int q = 0; q < 4; ++q) { const size_t i = i0 + q * NT < NCP ? i0 + q * NT : i0, n = i / RW, w = i % RW; d[q] = n * (CW - 1) * MIXB + w * 4; v[q] = __builtin_nontemporal_load((const f32x4*)(sc + d[q] + DS * MIXB)); }
; #pragma unroll
;           for (int q = 0; q < 4; ++q) __builtin_nontemporal_store(v[q], (f32x4*)(scs + d[q])); } }
.LBB0_87:
	s_or_b64 exec, exec, s[6:7]
	v_readlane_b32 s8, v247, 16
	v_readlane_b32 s12, v247, 20
	v_readlane_b32 s13, v247, 21
	v_readlane_b32 s14, v247, 22
	v_readlane_b32 s15, v247, 23
	v_readlane_b32 s20, v247, 28
	v_readlane_b32 s21, v247, 29
	v_readlane_b32 s22, v247, 30
	v_readlane_b32 s23, v247, 31
	s_mov_b64 s[12:13], s[20:21]
	s_mov_b64 s[14:15], s[22:23]
	v_readlane_b32 s9, v247, 17
	s_add_u32 s8, s14, 0x6478000
	s_mov_b64 s[6:7], 0x68000
	v_readlane_b32 s10, v247, 18
	v_readlane_b32 s11, v247, 19
	s_addc_u32 s9, s15, 0
	v_cmp_gt_u64_e32 vcc, s[6:7], v[0:1]
	v_readlane_b32 s16, v247, 24
	v_readlane_b32 s17, v247, 25
	v_readlane_b32 s18, v247, 26
	v_readlane_b32 s19, v247, 27
	s_and_saveexec_b64 s[10:11], vcc
	v_readlane_b32 s12, v247, 0
	v_readlane_b32 s22, v247, 10
	v_readlane_b32 s23, v247, 11
	v_readlane_b32 s13, v247, 1
	v_readlane_b32 s14, v247, 2
	v_readlane_b32 s15, v247, 3
	v_readlane_b32 s16, v247, 4
	v_readlane_b32 s17, v247, 5
	v_readlane_b32 s18, v247, 6
	v_readlane_b32 s19, v247, 7
	v_readlane_b32 s20, v247, 8
	v_readlane_b32 s21, v247, 9
	v_readlane_b32 s24, v247, 12
	v_readlane_b32 s25, v247, 13
	v_readlane_b32 s26, v247, 14
	v_readlane_b32 s27, v247, 15
	s_cmp_eq_u32 s66, 0x100
	s_cbranch_scc1 .LBB0_90
	s_cbranch_execz .LBB0_90
	s_mov_b64 s[12:13], 0
	s_mov_b32 s0, 0x4ec4ec4f
	s_movk_i32 s1, 0xd00
	s_movk_i32 s3, 0x3c00
	v_mov_b32_e32 v3, 0
	s_movk_i32 s16, 0x2000
	s_mov_b32 s17, 0xc4ec4ec5
	s_mov_b32 s18, 0x4ec4ec4e
	s_mov_b64 s[14:15], 0x67fff

; __device__ __forceinline__ unsigned cvt_pk_bf16(float lo, float hi) { unsigned r; asm volatile("v_cvt_pk_bf16_f32 %0, %1, %2" : "=v"(r) : "v"(lo), "v"(hi)); return r; }
; __device__ __forceinline__ void p0_prologue(const Params& p, unsigned char* lds) {
;     ...
;     { bf16_t* PB = (bf16_t*)(ws + WS_PB); constexpr size_t NPB = (size_t)MT * DPLE / 8;
;       for (size_t i0 = gt; i0 < NPB; i0 += 4 * NT) { f32x4 a[4], b[4]; size_t e[4];
; #pragma unroll
;           for (int q = 0; q < 4; ++q) { const size_t i = i0 + q * NT < NPB ? i0 + q * NT : i0; e[q] = i * 8; const float* s = e[q] < (size_t)MP * DPLE ? p.in[I_PP] + e[q] : p.in[I_PS] + (e[q] - (size_t)MP * DPLE);
;               a[q] = __builtin_nontemporal_load((const f32x4*)s); b[q] = __builtin_nontemporal_load((const f32x4*)(s + 4)); }
; #pragma unroll
;           for (int q = 0; q < 4; ++q) { u32x4 w; w.x = cvt_pk_bf16(a[q][0], a[q][1]); w.y = cvt_pk_bf16(a[q][2], a[q][3]); w.z = cvt_pk_bf16(b[q][0], b[q][1]); w.w = cvt_pk_bf16(b[q][2], b[q][3]); *(u32x4*)(PB + e[q]) = w; } } }
.LBB0_708:
	s_cmp_lg_u32 s66, 0x100
	s_cbranch_scc1 .Ltail_done
	s_cmp_lt_u32 s2, 172
	s_cbranch_scc1 .Ltail_done
	s_sub_u32 s0, s2, 172
	v_readfirstlane_b32 s1, v176
	s_nop 3
	s_lshr_b32 s1, s1, 6
	s_lshl_b32 s3, s0, 3
	s_add_u32 s3, s3, s1
	v_lshlrev_b32_e32 v120, 5, v206
	v_lshlrev_b32_e32 v121, 4, v206
	v_readlane_b32 s4, v247, 4
	v_readlane_b32 s5, v247, 5
	v_readlane_b32 s6, v247, 6
	v_readlane_b32 s7, v247, 7
	s_add_u32 s8, s64, 0x1b35e00
	s_addc_u32 s9, s65, 0
	s_mul_i32 s10, s3, 12
	s_min_u32 s11, s3, 0x180
	s_add_u32 s10, s10, s11
	s_cmp_lt_u32 s3, 0x180
	s_cbranch_scc0 .Ltail_pb12
	s_add_u32 s39, s10, 0
	s_cmp_lt_u32 s39, 0x2000
	s_cselect_b32 s12, s4, s6
	s_cselect_b32 s13, s5, s7
	s_cselect_b32 s38, 0, 0x2000
	s_sub_u32 s38, s39, s38
	s_lshl_b32 s38, s38, 11
	s_add_u32 s12, s12, s38
	s_addc_u32 s13, s13, 0
	global_load_dwordx4 v[0:3], v120, s[12:13]
	global_load_dwordx4 v[4:7], v120, s[12:13] offset:16
	s_add_u32 s39, s10, 1
	s_cmp_lt_u32 s39, 0x2000
	s_cselect_b32 s12, s4, s6
	s_cselect_b32 s13, s5, s7
	s_cselect_b32 s38, 0, 0x2000
	s_sub_u32 s38, s39, s38
	s_lshl_b32 s38, s38, 11
	s_add_u32 s12, s12, s38
	s_addc_u32 s13, s13, 0
	global_load_dwordx4 v[8:11], v120, s[12:13]
	global_load_dwordx4 v[12:15], v120, s[12:13] offset:16
	s_add_u32 s39, s10, 2
	s_cmp_lt_u32 s39, 0x2000
	s_cselect_b32 s12, s4, s6
	s_cselect_b32 s13, s5, s7
	s_cselect_b32 s38, 0, 0x2000
	s_sub_u32 s38, s39, s38
	s_lshl_b32 s38, s38, 11
	s_add_u32 s12, s12, s38
	s_addc_u32 s13, s13, 0
	global_load_dwordx4 v[16:19], v120, s[12:13]
	global_load_dwordx4 v[20:23], v120, s[12:13] offset:16
	s_add_u32 s39, s10, 3
	s_cmp_lt_u32 s39, 0x2000
	s_cselect_b32 s12, s4, s6
	s_cselect_b32 s13, s5, s7
	s_cselect_b32 s38, 0, 0x2000
	s_sub_u32 s38, s39, s38
	s_lshl_b32 s38, s38, 11
	s_add_u32 s12, s12, s38
	s_addc_u32 s13, s13, 0
	global_load_dwordx4 v[24:27], v120, s[12:13]
	global_load_dwordx4 v[28:31], v120, s[12:13] offset:16
	s_add_u32 s39, s10, 4
	s_cmp_lt_u32 s39, 0x2000
	s_cselect_b32 s12, s4, s6
	s_cselect_b32 s13, s5, s7
	s_cselect_b32 s38, 0, 0x2000
	s_sub_u32 s38, s39, s38
	s_lshl_b32 s38, s38, 11
	s_add_u32 s12, s12, s38
	s_addc_u32 s13, s13, 0
	global_load_dwordx4 v[32:35], v120, s[12:13]
	global_load_dwordx4 v[36:39], v120, s[12:13] offset:16
	s_add_u32 s39, s10, 5
	s_cmp_lt_u32 s39, 0x2000
	s_cselect_b32 s12, s4, s6
	s_cselect_b32 s13, s5, s7
	s_cselect_b32 s38, 0, 0x2000
	s_sub_u32 s38, s39, s38
	s_lshl_b32 s38, s38, 11
	s_add_u32 s12, s12, s38
	s_addc_u32 s13, s13, 0
	global_load_dwordx4 v[40:43], v120, s[12:13]
	global_load_dwordx4 v[44:47], v120, s[12:13] offset:16
	s_add_u32 s39, s10, 6
	s_cmp_lt_u32 s39, 0x2000
	s_cselect_b32 s12, s4, s6
	s_cselect_b32 s13, s5, s7
	s_cselect_b32 s38, 0, 0x2000
	s_sub_u32 s38, s39, s38
	s_lshl_b32 s38, s38, 11
	s_add_u32 s12, s12, s38
	s_addc_u32 s13, s13, 0
	global_load_dwordx4 v[48:51], v120, s[12:13]
	global_load_dwordx4 v[52:55], v120, s[12:13] offset:16
	s_add_u32 s39, s10, 7
	s_cmp_lt_u32 s39, 0x2000
	s_cselect_b32 s12, s4, s6
	s_cselect_b32 s13, s5, s7
	s_cselect_b32 s38, 0, 0x2000
	s_sub_u32 s38, s39, s38
	s_lshl_b32 s38, s38, 11
	s_add_u32 s12, s12, s38
	s_addc_u32 s13, s13, 0
	global_load_dwordx4 v[56:59], v120, s[12:13]
	global_load_dwordx4 v[60:63], v120, s[12:13] offset:16
	s_add_u32 s39, s10, 8
	s_cmp_lt_u32 s39, 0x2000
	s_cselect_b32 s12, s4, s6
	s_cselect_b32 s13, s5, s7
	s_cselect_b32 s38, 0, 0x2000
	s_sub_u32 s38, s39, s38
	s_lshl_b32 s38, s38, 11
	s_add_u32 s12, s12, s38
	s_addc_u32 s13, s13, 0
	global_load_dwordx4 v[64:67], v120, s[12:13]
	global_load_dwordx4 v[68:71], v120, s[12:13] offset:16
	s_add_u32 s39, s10, 9
	s_cmp_lt_u32 s39, 0x2000
	s_cselect_b32 s12, s4, s6
	s_cselect_b32 s13, s5, s7
	s_cselect_b32 s38, 0, 0x2000
	s_sub_u32 s38, s39, s38
	s_lshl_b32 s38, s38, 11
	s_add_u32 s12, s12, s38
	s_addc_u32 s13, s13, 0
	global_load_dwordx4 v[72:75], v120, s[12:13]
	global_load_dwordx4 v[76:79], v120, s[12:13] offset:16
	s_add_u32 s39, s10, 10
	s_cmp_lt_u32 s39, 0x2000
	s_cselect_b32 s12, s4, s6
	s_cselect_b32 s13, s5, s7
	s_cselect_b32 s38, 0, 0x2000
	s_sub_u32 s38, s39, s38
	s_lshl_b32 s38, s38, 11
	s_add_u32 s12, s12, s38
	s_addc_u32 s13, s13, 0
	global_load_dwordx4 v[80:83], v120, s[12:13]
	global_load_dwordx4 v[84:87], v120, s[12:13] offset:16
	s_add_u32 s39, s10, 11
	s_cmp_lt_u32 s39, 0x2000
	s_cselect_b32 s12, s4, s6
	s_cselect_b32 s13, s5, s7
	s_cselect_b32 s38, 0, 0x2000
	s_sub_u32 s38, s39, s38
	s_lshl_b32 s38, s38, 11
	s_add_u32 s12, s12, s38
	s_addc_u32 s13, s13, 0
	global_load_dwordx4 v[88:91], v120, s[12:13]
	global_load_dwordx4 v[92:95], v120, s[12:13] offset:16
	s_add_u32 s39, s10, 12
	s_cmp_lt_u32 s39, 0x2000
	s_cselect_b32 s12, s4, s6
	s_cselect_b32 s13, s5, s7
	s_cselect_b32 s38, 0, 0x2000
	s_sub_u32 s38, s39, s38
	s_lshl_b32 s38, s38, 11
	s_add_u32 s12, s12, s38
	s_addc_u32 s13, s13, 0
	global_load_dwordx4 v[96:99], v120, s[12:13]
	global_load_dwordx4 v[100:103], v120, s[12:13] offset:16
	s_waitcnt vmcnt(24)
	v_cvt_pk_bf16_f32 v0, v0, v1
	v_cvt_pk_bf16_f32 v1, v2, v3
	v_cvt_pk_bf16_f32 v2, v4, v5
	v_cvt_pk_bf16_f32 v3, v6, v7
	s_add_u32 s39, s10, 0
	s_lshl_b32 s38, s39, 10
	s_add_u32 s40, s8, s38
	s_addc_u32 s41, s9, 0
	global_store_dwordx4 v121, v[0:3], s[40:41]
	s_waitcnt vmcnt(23)
	v_cvt_pk_bf16_f32 v8, v8, v9
	v_cvt_pk_bf16_f32 v9, v10, v11
	v_cvt_pk_bf16_f32 v10, v12, v13
	v_cvt_pk_bf16_f32 v11, v14, v15
	s_add_u32 s39, s10, 1
	s_lshl_b32 s38, s39, 10
	s_add_u32 s40, s8, s38
	s_addc_u32 s41, s9, 0
	global_store_dwordx4 v121, v[8:11], s[40:41]
	s_waitcnt vmcnt(22)
; __device__ __forceinline__ unsigned cvt_pk_bf16(float lo, float hi) { unsigned r; asm volatile("v_cvt_pk_bf16_f32 %0, %1, %2" : "=v"(r) : "v"(lo), "v"(hi)); return r; }
; __device__ __forceinline__ void p0_prologue(const Params& p, unsigned char* lds) {
;     ...
;     { bf16_t* PB = (bf16_t*)(ws + WS_PB); constexpr size_t NPB = (size_t)MT * DPLE / 8;
;       for (size_t i0 = gt; i0 < NPB; i0 += 4 * NT) { f32x4 a[4], b[4]; size_t e[4];
; #pragma unroll
;           for (int q = 0; q < 4; ++q) { const size_t i = i0 + q * NT < NPB ? i0 + q * NT : i0; e[q] = i * 8; const float* s = e[q] < (size_t)MP * DPLE ? p.in[I_PP] + e[q] : p.in[I_PS] + (e[q] - (size_t)MP * DPLE);
;               a[q] = __builtin_nontemporal_load((const f32x4*)s); b[q] = __builtin_nontemporal_load((const f32x4*)(s + 4)); }
; #pragma unroll
;           for (int q = 0; q < 4; ++q) { u32x4 w; w.x = cvt_pk_bf16(a[q][0], a[q][1]); w.y = cvt_pk_bf16(a[q][2], a[q][3]); w.z = cvt_pk_bf16(b[q][0], b[q][1]); w.w = cvt_pk_bf16(b[q][2], b[q][3]); *(u32x4*)(PB + e[q]) = w; } } }
	v_cvt_pk_bf16_f32 v16, v16, v17
	v_cvt_pk_bf16_f32 v17, v18, v19
	v_cvt_pk_bf16_f32 v18, v20, v21
	v_cvt_pk_bf16_f32 v19, v22, v23
	s_add_u32 s39, s10, 2
	s_lshl_b32 s38, s39, 10
	s_add_u32 s40, s8, s38
	s_addc_u32 s41, s9, 0
	global_store_dwordx4 v121, v[16:19], s[40:41]
	s_waitcnt vmcnt(21)
	v_cvt_pk_bf16_f32 v24, v24, v25
	v_cvt_pk_bf16_f32 v25, v26, v27
	v_cvt_pk_bf16_f32 v26, v28, v29
	v_cvt_pk_bf16_f32 v27, v30, v31
	s_add_u32 s39, s10, 3
	s_lshl_b32 s38, s39, 10
	s_add_u32 s40, s8, s38
	s_addc_u32 s41, s9, 0
	global_store_dwordx4 v121, v[24:27], s[40:41]
	s_waitcnt vmcnt(20)
	v_cvt_pk_bf16_f32 v32, v32, v33
	v_cvt_pk_bf16_f32 v33, v34, v35
	v_cvt_pk_bf16_f32 v34, v36, v37
	v_cvt_pk_bf16_f32 v35, v38, v39
	s_add_u32 s39, s10, 4
	s_lshl_b32 s38, s39, 10
	s_add_u32 s40, s8, s38
	s_addc_u32 s41, s9, 0
	global_store_dwordx4 v121, v[32:35], s[40:41]
	s_waitcnt vmcnt(19)
	v_cvt_pk_bf16_f32 v40, v40, v41
	v_cvt_pk_bf16_f32 v41, v42, v43
	v_cvt_pk_bf16_f32 v42, v44, v45
	v_cvt_pk_bf16_f32 v43, v46, v47
	s_add_u32 s39, s10, 5
	s_lshl_b32 s38, s39, 10
	s_add_u32 s40, s8, s38
	s_addc_u32 s41, s9, 0
	global_store_dwordx4 v121, v[40:43], s[40:41]
	s_waitcnt vmcnt(18)
	v_cvt_pk_bf16_f32 v48, v48, v49
	v_cvt_pk_bf16_f32 v49, v50, v51
	v_cvt_pk_bf16_f32 v50, v52, v53
	v_cvt_pk_bf16_f32 v51, v54, v55
	s_add_u32 s39, s10, 6
	s_lshl_b32 s38, s39, 10
	s_add_u32 s40, s8, s38
	s_addc_u32 s41, s9, 0
	global_store_dwordx4 v121, v[48:51], s[40:41]
	s_waitcnt vmcnt(17)
	v_cvt_pk_bf16_f32 v56, v56, v57
	v_cvt_pk_bf16_f32 v57, v58, v59
	v_cvt_pk_bf16_f32 v58, v60, v61
	v_cvt_pk_bf16_f32 v59, v62, v63
	s_add_u32 s39, s10, 7
	s_lshl_b32 s38, s39, 10
	s_add_u32 s40, s8, s38
	s_addc_u32 s41, s9, 0
	global_store_dwordx4 v121, v[56:59], s[40:41]
	s_waitcnt vmcnt(16)
	v_cvt_pk_bf16_f32 v64, v64, v65
	v_cvt_pk_bf16_f32 v65, v66, v67
	v_cvt_pk_bf16_f32 v66, v68, v69
	v_cvt_pk_bf16_f32 v67, v70, v71
	s_add_u32 s39, s10, 8
	s_lshl_b32 s38, s39, 10
	s_add_u32 s40, s8, s38
	s_addc_u32 s41, s9, 0
	global_store_dwordx4 v121, v[64:67], s[40:41]
	s_waitcnt vmcnt(15)
	v_cvt_pk_bf16_f32 v72, v72, v73
	v_cvt_pk_bf16_f32 v73, v74, v75
	v_cvt_pk_bf16_f32 v74, v76, v77
	v_cvt_pk_bf16_f32 v75, v78, v79
	s_add_u32 s39, s10, 9
	s_lshl_b32 s38, s39, 10
	s_add_u32 s40, s8, s38
	s_addc_u32 s41, s9, 0
	global_store_dwordx4 v121, v[72:75], s[40:41]
	s_waitcnt vmcnt(14)
	v_cvt_pk_bf16_f32 v80, v80, v81
	v_cvt_pk_bf16_f32 v81, v82, v83
	v_cvt_pk_bf16_f32 v82, v84, v85
	v_cvt_pk_bf16_f32 v83, v86, v87
	s_add_u32 s39, s10, 10
	s_lshl_b32 s38, s39, 10
	s_add_u32 s40, s8, s38
	s_addc_u32 s41, s9, 0
	global_store_dwordx4 v121, v[80:83], s[40:41]
	s_waitcnt vmcnt(13)
	v_cvt_pk_bf16_f32 v88, v88, v89
	v_cvt_pk_bf16_f32 v89, v90, v91
	v_cvt_pk_bf16_f32 v90, v92, v93
	v_cvt_pk_bf16_f32 v91, v94, v95
	s_add_u32 s39, s10, 11
	s_lshl_b32 s38, s39, 10
	s_add_u32 s40, s8, s38
	s_addc_u32 s41, s9, 0
	global_store_dwordx4 v121, v[88:91], s[40:41]
	s_waitcnt vmcnt(12)
	v_cvt_pk_bf16_f32 v96, v96, v97
	v_cvt_pk_bf16_f32 v97, v98, v99
	v_cvt_pk_bf16_f32 v98, v100, v101
	v_cvt_pk_bf16_f32 v99, v102, v103
	s_add_u32 s39, s10, 12
	s_lshl_b32 s38, s39, 10
	s_add_u32 s40, s8, s38
	s_addc_u32 s41, s9, 0
	global_store_dwordx4 v121, v[96:99], s[40:41]
	s_branch .Ltail_pb_done
.Ltail_pb12:
	s_add_u32 s39, s10, 0
	s_cmp_lt_u32 s39, 0x2000
	s_cselect_b32 s12, s4, s6
	s_cselect_b32 s13, s5, s7
	s_cselect_b32 s38, 0, 0x2000
	s_sub_u32 s38, s39, s38
	s_lshl_b32 s38, s38, 11
	s_add_u32 s12, s12, s38
	s_addc_u32 s13, s13, 0
	global_load_dwordx4 v[0:3], v120, s[12:13]
	global_load_dwordx4 v[4:7], v120, s[12:13] offset:16
	s_add_u32 s39, s10, 1
	s_cmp_lt_u32 s39, 0x2000
	s_cselect_b32 s12, s4, s6
	s_cselect_b32 s13, s5, s7
	s_cselect_b32 s38, 0, 0x2000
	s_sub_u32 s38, s39, s38
	s_lshl_b32 s38, s38, 11
	s_add_u32 s12, s12, s38
	s_addc_u32 s13, s13, 0
	global_load_dwordx4 v[8:11], v120, s[12:13]
	global_load_dwordx4 v[12:15], v120, s[12:13] offset:16
	s_add_u32 s39, s10, 2
	s_cmp_lt_u32 s39, 0x2000
	s_cselect_b32 s12, s4, s6
	s_cselect_b32 s13, s5, s7
	s_cselect_b32 s38, 0, 0x2000
	s_sub_u32 s38, s39, s38
	s_lshl_b32 s38, s38, 11
	s_add_u32 s12, s12, s38
	s_addc_u32 s13, s13, 0
	global_load_dwordx4 v[16:19], v120, s[12:13]
	global_load_dwordx4 v[20:23], v120, s[12:13] offset:16
	s_add_u32 s39, s10, 3
	s_cmp_lt_u32 s39, 0x2000
	s_cselect_b32 s12, s4, s6
	s_cselect_b32 s13, s5, s7
	s_cselect_b32 s38, 0, 0x2000
	s_sub_u32 s38, s39, s38
	s_lshl_b32 s38, s38, 11
	s_add_u32 s12, s12, s38
	s_addc_u32 s13, s13, 0
	global_load_dwordx4 v[24:27], v120, s[12:13]
	global_load_dwordx4 v[28:31], v120, s[12:13] offset:16
	s_add_u32 s39, s10, 4
	s_cmp_lt_u32 s39, 0x2000
	s_cselect_b32 s12, s4, s6
	s_cselect_b32 s13, s5, s7
	s_cselect_b32 s38, 0, 0x2000
	s_sub_u32 s38, s39, s38
	s_lshl_b32 s38, s38, 11
	s_add_u32 s12, s12, s38
	s_addc_u32 s13, s13, 0
	global_load_dwordx4 v[32:35], v120, s[12:13]
	global_load_dwordx4 v[36:39], v120, s[12:13] offset:16
	s_add_u32 s39, s10, 5
	s_cmp_lt_u32 s39, 0x2000
	s_cselect_b32 s12, s4, s6
	s_cselect_b32 s13, s5, s7
	s_cselect_b32 s38, 0, 0x2000
	s_sub_u32 s38, s39, s38
	s_lshl_b32 s38, s38, 11
	s_add_u32 s12, s12, s38
	s_addc_u32 s13, s13, 0
	global_load_dwordx4 v[40:43], v120, s[12:13]
	global_load_dwordx4 v[44:47], v120, s[12:13] offset:16
	s_add_u32 s39, s10, 6
	s_cmp_lt_u32 s39, 0x2000
	s_cselect_b32 s12, s4, s6
	s_cselect_b32 s13, s5, s7
	s_cselect_b32 s38, 0, 0x2000
	s_sub_u32 s38, s39, s38
	s_lshl_b32 s38, s38, 11
	s_add_u32 s12, s12, s38
	s_addc_u32 s13, s13, 0
	global_load_dwordx4 v[48:51], v120, s[12:13]
	global_load_dwordx4 v[52:55], v120, s[12:13] offset:16
	s_add_u32 s39, s10, 7
	s_cmp_lt_u32 s39, 0x2000
; __device__ __forceinline__ unsigned cvt_pk_bf16(float lo, float hi) { unsigned r; asm volatile("v_cvt_pk_bf16_f32 %0, %1, %2" : "=v"(r) : "v"(lo), "v"(hi)); return r; }
; __device__ __forceinline__ void p0_prologue(const Params& p, unsigned char* lds) {
;     ...
;     { bf16_t* PB = (bf16_t*)(ws + WS_PB); constexpr size_t NPB = (size_t)MT * DPLE / 8;
;       for (size_t i0 = gt; i0 < NPB; i0 += 4 * NT) { f32x4 a[4], b[4]; size_t e[4];
; #pragma unroll
;           for (int q = 0; q < 4; ++q) { const size_t i = i0 + q * NT < NPB ? i0 + q * NT : i0; e[q] = i * 8; const float* s = e[q] < (size_t)MP * DPLE ? p.in[I_PP] + e[q] : p.in[I_PS] + (e[q] - (size_t)MP * DPLE);
;               a[q] = __builtin_nontemporal_load((const f32x4*)s); b[q] = __builtin_nontemporal_load((const f32x4*)(s + 4)); }
; #pragma unroll
;           for (int q = 0; q < 4; ++q) { u32x4 w; w.x = cvt_pk_bf16(a[q][0], a[q][1]); w.y = cvt_pk_bf16(a[q][2], a[q][3]); w.z = cvt_pk_bf16(b[q][0], b[q][1]); w.w = cvt_pk_bf16(b[q][2], b[q][3]); *(u32x4*)(PB + e[q]) = w; } } }
	s_cselect_b32 s12, s4, s6
	s_cselect_b32 s13, s5, s7
	s_cselect_b32 s38, 0, 0x2000
	s_sub_u32 s38, s39, s38
	s_lshl_b32 s38, s38, 11
	s_add_u32 s12, s12, s38
	s_addc_u32 s13, s13, 0
	global_load_dwordx4 v[56:59], v120, s[12:13]
	global_load_dwordx4 v[60:63], v120, s[12:13] offset:16
	s_add_u32 s39, s10, 8
	s_cmp_lt_u32 s39, 0x2000
	s_cselect_b32 s12, s4, s6
	s_cselect_b32 s13, s5, s7
	s_cselect_b32 s38, 0, 0x2000
	s_sub_u32 s38, s39, s38
	s_lshl_b32 s38, s38, 11
	s_add_u32 s12, s12, s38
	s_addc_u32 s13, s13, 0
	global_load_dwordx4 v[64:67], v120, s[12:13]
	global_load_dwordx4 v[68:71], v120, s[12:13] offset:16
	s_add_u32 s39, s10, 9
	s_cmp_lt_u32 s39, 0x2000
	s_cselect_b32 s12, s4, s6
	s_cselect_b32 s13, s5, s7
	s_cselect_b32 s38, 0, 0x2000
	s_sub_u32 s38, s39, s38
	s_lshl_b32 s38, s38, 11
	s_add_u32 s12, s12, s38
	s_addc_u32 s13, s13, 0
	global_load_dwordx4 v[72:75], v120, s[12:13]
	global_load_dwordx4 v[76:79], v120, s[12:13] offset:16
	s_add_u32 s39, s10, 10
	s_cmp_lt_u32 s39, 0x2000
	s_cselect_b32 s12, s4, s6
	s_cselect_b32 s13, s5, s7
	s_cselect_b32 s38, 0, 0x2000
	s_sub_u32 s38, s39, s38
	s_lshl_b32 s38, s38, 11
	s_add_u32 s12, s12, s38
	s_addc_u32 s13, s13, 0
	global_load_dwordx4 v[80:83], v120, s[12:13]
	global_load_dwordx4 v[84:87], v120, s[12:13] offset:16
	s_add_u32 s39, s10, 11
	s_cmp_lt_u32 s39, 0x2000
	s_cselect_b32 s12, s4, s6
	s_cselect_b32 s13, s5, s7
	s_cselect_b32 s38, 0, 0x2000
	s_sub_u32 s38, s39, s38
	s_lshl_b32 s38, s38, 11
	s_add_u32 s12, s12, s38
	s_addc_u32 s13, s13, 0
	global_load_dwordx4 v[88:91], v120, s[12:13]
	global_load_dwordx4 v[92:95], v120, s[12:13] offset:16
	s_waitcnt vmcnt(22)
	v_cvt_pk_bf16_f32 v0, v0, v1
	v_cvt_pk_bf16_f32 v1, v2, v3
	v_cvt_pk_bf16_f32 v2, v4, v5
	v_cvt_pk_bf16_f32 v3, v6, v7
	s_add_u32 s39, s10, 0
	s_lshl_b32 s38, s39, 10
	s_add_u32 s40, s8, s38
	s_addc_u32 s41, s9, 0
	global_store_dwordx4 v121, v[0:3], s[40:41]
	s_waitcnt vmcnt(21)
	v_cvt_pk_bf16_f32 v8, v8, v9
	v_cvt_pk_bf16_f32 v9, v10, v11
	v_cvt_pk_bf16_f32 v10, v12, v13
	v_cvt_pk_bf16_f32 v11, v14, v15
	s_add_u32 s39, s10, 1
	s_lshl_b32 s38, s39, 10
	s_add_u32 s40, s8, s38
	s_addc_u32 s41, s9, 0
	global_store_dwordx4 v121, v[8:11], s[40:41]
	s_waitcnt vmcnt(20)
	v_cvt_pk_bf16_f32 v16, v16, v17
	v_cvt_pk_bf16_f32 v17, v18, v19
	v_cvt_pk_bf16_f32 v18, v20, v21
	v_cvt_pk_bf16_f32 v19, v22, v23
	s_add_u32 s39, s10, 2
	s_lshl_b32 s38, s39, 10
	s_add_u32 s40, s8, s38
	s_addc_u32 s41, s9, 0
	global_store_dwordx4 v121, v[16:19], s[40:41]
	s_waitcnt vmcnt(19)
	v_cvt_pk_bf16_f32 v24, v24, v25
	v_cvt_pk_bf16_f32 v25, v26, v27
	v_cvt_pk_bf16_f32 v26, v28, v29
	v_cvt_pk_bf16_f32 v27, v30, v31
	s_add_u32 s39, s10, 3
	s_lshl_b32 s38, s39, 10
	s_add_u32 s40, s8, s38
	s_addc_u32 s41, s9, 0
	global_store_dwordx4 v121, v[24:27], s[40:41]
	s_waitcnt vmcnt(18)
	v_cvt_pk_bf16_f32 v32, v32, v33
	v_cvt_pk_bf16_f32 v33, v34, v35
	v_cvt_pk_bf16_f32 v34, v36, v37
	v_cvt_pk_bf16_f32 v35, v38, v39
	s_add_u32 s39, s10, 4
	s_lshl_b32 s38, s39, 10
	s_add_u32 s40, s8, s38
	s_addc_u32 s41, s9, 0
	global_store_dwordx4 v121, v[32:35], s[40:41]
	s_waitcnt vmcnt(17)
	v_cvt_pk_bf16_f32 v40, v40, v41
	v_cvt_pk_bf16_f32 v41, v42, v43
	v_cvt_pk_bf16_f32 v42, v44, v45
	v_cvt_pk_bf16_f32 v43, v46, v47
	s_add_u32 s39, s10, 5
	s_lshl_b32 s38, s39, 10
	s_add_u32 s40, s8, s38
	s_addc_u32 s41, s9, 0
	global_store_dwordx4 v121, v[40:43], s[40:41]
	s_waitcnt vmcnt(16)
	v_cvt_pk_bf16_f32 v48, v48, v49
	v_cvt_pk_bf16_f32 v49, v50, v51
	v_cvt_pk_bf16_f32 v50, v52, v53
	v_cvt_pk_bf16_f32 v51, v54, v55
	s_add_u32 s39, s10, 6
	s_lshl_b32 s38, s39, 10
	s_add_u32 s40, s8, s38
	s_addc_u32 s41, s9, 0
	global_store_dwordx4 v121, v[48:51], s[40:41]
	s_waitcnt vmcnt(15)
	v_cvt_pk_bf16_f32 v56, v56, v57
	v_cvt_pk_bf16_f32 v57, v58, v59
	v_cvt_pk_bf16_f32 v58, v60, v61
	v_cvt_pk_bf16_f32 v59, v62, v63
	s_add_u32 s39, s10, 7
	s_lshl_b32 s38, s39, 10
	s_add_u32 s40, s8, s38
	s_addc_u32 s41, s9, 0
	global_store_dwordx4 v121, v[56:59], s[40:41]
	s_waitcnt vmcnt(14)
	v_cvt_pk_bf16_f32 v64, v64, v65
	v_cvt_pk_bf16_f32 v65, v66, v67
	v_cvt_pk_bf16_f32 v66, v68, v69
	v_cvt_pk_bf16_f32 v67, v70, v71
	s_add_u32 s39, s10, 8
	s_lshl_b32 s38, s39, 10
	s_add_u32 s40, s8, s38
	s_addc_u32 s41, s9, 0
	global_store_dwordx4 v121, v[64:67], s[40:41]
	s_waitcnt vmcnt(13)
	v_cvt_pk_bf16_f32 v72, v72, v73
	v_cvt_pk_bf16_f32 v73, v74, v75
	v_cvt_pk_bf16_f32 v74, v76, v77
	v_cvt_pk_bf16_f32 v75, v78, v79
	s_add_u32 s39, s10, 9
	s_lshl_b32 s38, s39, 10
	s_add_u32 s40, s8, s38
	s_addc_u32 s41, s9, 0
	global_store_dwordx4 v121, v[72:75], s[40:41]
	s_waitcnt vmcnt(12)
	v_cvt_pk_bf16_f32 v80, v80, v81
	v_cvt_pk_bf16_f32 v81, v82, v83
	v_cvt_pk_bf16_f32 v82, v84, v85
	v_cvt_pk_bf16_f32 v83, v86, v87
	s_add_u32 s39, s10, 10
	s_lshl_b32 s38, s39, 10
	s_add_u32 s40, s8, s38
	s_addc_u32 s41, s9, 0
	global_store_dwordx4 v121, v[80:83], s[40:41]
	s_waitcnt vmcnt(11)
	v_cvt_pk_bf16_f32 v88, v88, v89
	v_cvt_pk_bf16_f32 v89, v90, v91
	v_cvt_pk_bf16_f32 v90, v92, v93
	v_cvt_pk_bf16_f32 v91, v94, v95
	s_add_u32 s39, s10, 11
	s_lshl_b32 s38, s39, 10
	s_add_u32 s40, s8, s38
	s_addc_u32 s41, s9, 0
	global_store_dwordx4 v121, v[88:91], s[40:41]
; __device__ __forceinline__ unsigned cvt_pk_bf16(float lo, float hi) { unsigned r; asm volatile("v_cvt_pk_bf16_f32 %0, %1, %2" : "=v"(r) : "v"(lo), "v"(hi)); return r; }
; __device__ __forceinline__ void tr_load(const TrItem& t, int lane, f32x4 (&v)[8], f32x4 (&g)[2]) {
;     const int r = lane & 7, k0 = 64 * t.kb + 8 * (lane >> 3); const float* src = t.W + (size_t)k0 * t.ldw + t.sc0 + 4 * r;
; #pragma unroll
;     for (int i = 0; i < 8; ++i) v[i] = __builtin_nontemporal_load((const f32x4*)(src + (size_t)i * t.ldw));
;     if (t.gain) { g[0] = *(const f32x4*)(t.gain + k0); g[1] = *(const f32x4*)(t.gain + k0 + 4); } else { g[0] = (f32x4){1.f, 1.f, 1.f, 1.f}; g[1] = g[0]; }
; }
; __device__ __forceinline__ void tr_store(const TrItem& t, int lane, const f32x4 (&v)[8], const f32x4 (&g)[2]) {
;     const int r = lane & 7, k0 = 64 * t.kb + 8 * (lane >> 3); bf16_t* dst = t.WT + (size_t)(t.dr0 + 4 * r) * t.K + k0;
; #pragma unroll
;     for (int j = 0; j < 4; ++j) { u32x4 o; o.x = cvt_pk_bf16(v[0][j] * g[0][0], v[1][j] * g[0][1]); o.y = cvt_pk_bf16(v[2][j] * g[0][2], v[3][j] * g[0][3]);
;         o.z = cvt_pk_bf16(v[4][j] * g[1][0], v[5][j] * g[1][1]); o.w = cvt_pk_bf16(v[6][j] * g[1][2], v[7][j] * g[1][3]); *(u32x4*)(dst + (size_t)j * t.K) = o; }
; }
.Ltail_pb_done:
	v_readlane_b32 s4, v247, 20
	v_readlane_b32 s5, v247, 21
	v_readlane_b32 s6, v247, 22
	v_readlane_b32 s7, v247, 23
	v_readlane_b32 s8, v247, 24
	v_readlane_b32 s9, v247, 25
	v_readlane_b32 s10, v247, 26
	v_readlane_b32 s11, v247, 27
	v_and_b32_e32 v122, 7, v206
	v_lshrrev_b32_e32 v123, 3, v206
	v_lshlrev_b32_e32 v124, 15, v123
	v_lshl_add_u32 v124, v122, 4, v124
	v_add_u32_e32 v125, 0x1000, v124
	v_add_u32_e32 v126, 0x2000, v124
	v_add_u32_e32 v127, 0x3000, v124
	v_add_u32_e32 v128, 0x4000, v124
	v_add_u32_e32 v129, 0x5000, v124
	v_add_u32_e32 v130, 0x6000, v124
	v_add_u32_e32 v131, 0x7000, v124
	v_lshlrev_b32_e32 v132, 5, v123
	s_add_u32 s39, s3, 0
	s_cmp_lt_u32 s39, 0x580
	s_cbranch_scc0 .Ltw5_0
	s_mov_b32 s38, s39
	s_mov_b32 s12, s4
	s_mov_b32 s13, s5
	s_add_u32 s14, s64, 0x1300000
	s_addc_u32 s15, s65, 0
	s_movk_i32 s32, 0xb00
	s_mov_b32 s33, 0
	s_branch .Ltwgo_0
.Ltw5_0:
	s_cmp_lt_u32 s39, 0x780
	s_cbranch_scc0 .Ltw6_0
	s_sub_u32 s38, s39, 0x580
	s_mov_b32 s12, s8
	s_mov_b32 s13, s9
	s_add_u32 s14, s64, 0x1880000
	s_addc_u32 s15, s65, 0
	s_movk_i32 s32, 0x400
	s_mov_b32 s33, 1
	s_branch .Ltwgo_0
.Ltw6_0:
	s_sub_u32 s38, s39, 0x780
	s_mov_b32 s12, s10
	s_mov_b32 s13, s11
	s_add_u32 s14, s64, 0x1a80000
	s_addc_u32 s15, s65, 0
	s_movk_i32 s32, 0x100
	s_mov_b32 s33, 0
.Ltwgo_0:
	s_lshr_b32 s36, s38, 5
	s_and_b32 s37, s38, 31
	s_lshl_b32 s40, s36, 18
	s_lshl_b32 s41, s37, 7
	s_add_u32 s40, s40, s41
	s_add_u32 s12, s12, s40
	s_addc_u32 s13, s13, 0
	global_load_dwordx4 v[0:3], v124, s[12:13]
	global_load_dwordx4 v[4:7], v125, s[12:13]
	global_load_dwordx4 v[8:11], v126, s[12:13]
	global_load_dwordx4 v[12:15], v127, s[12:13]
	global_load_dwordx4 v[16:19], v128, s[12:13]
	global_load_dwordx4 v[20:23], v129, s[12:13]
	global_load_dwordx4 v[24:27], v130, s[12:13]
	global_load_dwordx4 v[28:31], v131, s[12:13]
	s_and_b32 s40, s36, 15
	s_lshl_b32 s40, s40, 8
	v_add_u32_e32 v40, s40, v132
	global_load_dwordx4 v[32:35], v40, s[6:7]
	global_load_dwordx4 v[36:39], v40, s[6:7] offset:16
	s_add_u32 s39, s3, 672
	s_cmp_lt_u32 s39, 0x580
	s_cbranch_scc0 .Ltw5_1
	s_mov_b32 s38, s39
	s_mov_b32 s42, s4
	s_mov_b32 s43, s5
	s_add_u32 s46, s64, 0x1300000
	s_addc_u32 s47, s65, 0
	s_movk_i32 s48, 0xb00
	s_mov_b32 s49, 0
	s_branch .Ltwgo_1
.Ltw5_1:
	s_cmp_lt_u32 s39, 0x780
	s_cbranch_scc0 .Ltw6_1
	s_sub_u32 s38, s39, 0x580
	s_mov_b32 s42, s8
	s_mov_b32 s43, s9
	s_add_u32 s46, s64, 0x1880000
	s_addc_u32 s47, s65, 0
	s_movk_i32 s48, 0x400
	s_mov_b32 s49, 1
	s_branch .Ltwgo_1
.Ltw6_1:
	s_sub_u32 s38, s39, 0x780
	s_mov_b32 s42, s10
	s_mov_b32 s43, s11
	s_add_u32 s46, s64, 0x1a80000
	s_addc_u32 s47, s65, 0
	s_movk_i32 s48, 0x100
	s_mov_b32 s49, 0
.Ltwgo_1:
	s_lshr_b32 s50, s38, 5
	s_and_b32 s51, s38, 31
	s_lshl_b32 s40, s50, 18
	s_lshl_b32 s41, s51, 7
	s_add_u32 s40, s40, s41
	s_add_u32 s42, s42, s40
	s_addc_u32 s43, s43, 0
	global_load_dwordx4 v[48:51], v124, s[42:43]
	global_load_dwordx4 v[52:55], v125, s[42:43]
	global_load_dwordx4 v[56:59], v126, s[42:43]
	global_load_dwordx4 v[60:63], v127, s[42:43]
	global_load_dwordx4 v[64:67], v128, s[42:43]
	global_load_dwordx4 v[68:71], v129, s[42:43]
	global_load_dwordx4 v[72:75], v130, s[42:43]
	global_load_dwordx4 v[76:79], v131, s[42:43]
	s_and_b32 s40, s50, 15
	s_lshl_b32 s40, s40, 8
	v_add_u32_e32 v88, s40, v132
	global_load_dwordx4 v[80:83], v88, s[6:7]
	global_load_dwordx4 v[84:87], v88, s[6:7] offset:16
	s_waitcnt vmcnt(10)
	s_cmp_eq_u32 s33, 1
	s_cbranch_scc1 .Ltwg_2
	v_mov_b32_e32 v32, 1.0
	v_mov_b32_e32 v33, 1.0
	v_mov_b32_e32 v34, 1.0
	v_mov_b32_e32 v35, 1.0
	v_mov_b32_e32 v36, 1.0
	v_mov_b32_e32 v37, 1.0
	v_mov_b32_e32 v38, 1.0
	v_mov_b32_e32 v39, 1.0
.Ltwg_2:
	s_lshl_b32 s40, s37, 5
	v_lshl_add_u32 v40, v122, 2, s40
	v_mul_lo_u32 v40, v40, s32
	s_lshl_b32 s40, s36, 6
	v_lshl_add_u32 v41, v123, 3, s40
	v_add_lshl_u32 v40, v40, v41, 1
	s_lshl_b32 s40, s32, 1
	v_mul_f32_e32 v0, v0, v32
	v_mul_f32_e32 v1, v1, v32
	v_mul_f32_e32 v2, v2, v32
	v_mul_f32_e32 v3, v3, v32
	v_mul_f32_e32 v4, v4, v33
	v_mul_f32_e32 v5, v5, v33
	v_mul_f32_e32 v6, v6, v33
	v_mul_f32_e32 v7, v7, v33
	v_mul_f32_e32 v8, v8, v34
	v_mul_f32_e32 v9, v9, v34
	v_mul_f32_e32 v10, v10, v34
	v_mul_f32_e32 v11, v11, v34
	v_mul_f32_e32 v12, v12, v35
	v_mul_f32_e32 v13, v13, v35
	v_mul_f32_e32 v14, v14, v35
	v_mul_f32_e32 v15, v15, v35
	v_mul_f32_e32 v16, v16, v36
	v_mul_f32_e32 v17, v17, v36
	v_mul_f32_e32 v18, v18, v36
	v_mul_f32_e32 v19, v19, v36
	v_mul_f32_e32 v20, v20, v37
	v_mul_f32_e32 v21, v21, v37
	v_mul_f32_e32 v22, v22, v37
	v_mul_f32_e32 v23, v23, v37
	v_mul_f32_e32 v24, v24, v38
	v_mul_f32_e32 v25, v25, v38
	v_mul_f32_e32 v26, v26, v38
	v_mul_f32_e32 v27, v27, v38
	v_mul_f32_e32 v28, v28, v39
	v_mul_f32_e32 v29, v29, v39
	v_mul_f32_e32 v30, v30, v39
	v_mul_f32_e32 v31, v31, v39
	v_cvt_pk_bf16_f32 v32, v0, v4
	v_cvt_pk_bf16_f32 v33, v8, v12
	v_cvt_pk_bf16_f32 v34, v16, v20
	v_cvt_pk_bf16_f32 v35, v24, v28
	global_store_dwordx4 v40, v[32:35], s[14:15]
	v_add_u32_e32 v40, s40, v40
	v_cvt_pk_bf16_f32 v36, v1, v5
	v_cvt_pk_bf16_f32 v37, v9, v13
	v_cvt_pk_bf16_f32 v38, v17, v21
	v_cvt_pk_bf16_f32 v39, v25, v29
	global_store_dwordx4 v40, v[36:39], s[14:15]
	v_add_u32_e32 v40, s40, v40
	s_nop 1
	v_cvt_pk_bf16_f32 v32, v2, v6
	v_cvt_pk_bf16_f32 v33, v10, v14
	v_cvt_pk_bf16_f32 v34, v18, v22
	v_cvt_pk_bf16_f32 v35, v26, v30
	global_store_dwordx4 v40, v[32:35], s[14:15]
	v_add_u32_e32 v40, s40, v40
	v_cvt_pk_bf16_f32 v36, v3, v7
	v_cvt_pk_bf16_f32 v37, v11, v15
	v_cvt_pk_bf16_f32 v38, v19, v23
	v_cvt_pk_bf16_f32 v39, v27, v31
	global_store_dwordx4 v40, v[36:39], s[14:15]
	s_add_u32 s39, s3, 1344
	s_cmp_lt_u32 s39, 0x580
	s_cbranch_scc0 .Ltw5_3
	s_mov_b32 s38, s39
	s_mov_b32 s12, s4
	s_mov_b32 s13, s5
	s_add_u32 s14, s64, 0x1300000
	s_addc_u32 s15, s65, 0
	s_movk_i32 s32, 0xb00
	s_mov_b32 s33, 0
	s_branch .Ltwgo_3

; __device__ __forceinline__ unsigned cvt_pk_bf16(float lo, float hi) { unsigned r; asm volatile("v_cvt_pk_bf16_f32 %0, %1, %2" : "=v"(r) : "v"(lo), "v"(hi)); return r; }
; __device__ __forceinline__ void tr_load(const TrItem& t, int lane, f32x4 (&v)[8], f32x4 (&g)[2]) {
;     const int r = lane & 7, k0 = 64 * t.kb + 8 * (lane >> 3); const float* src = t.W + (size_t)k0 * t.ldw + t.sc0 + 4 * r;
; #pragma unroll
;     for (int i = 0; i < 8; ++i) v[i] = __builtin_nontemporal_load((const f32x4*)(src + (size_t)i * t.ldw));
;     if (t.gain) { g[0] = *(const f32x4*)(t.gain + k0); g[1] = *(const f32x4*)(t.gain + k0 + 4); } else { g[0] = (f32x4){1.f, 1.f, 1.f, 1.f}; g[1] = g[0]; }
; }
; __device__ __forceinline__ void tr_store(const TrItem& t, int lane, const f32x4 (&v)[8], const f32x4 (&g)[2]) {
;     const int r = lane & 7, k0 = 64 * t.kb + 8 * (lane >> 3); bf16_t* dst = t.WT + (size_t)(t.dr0 + 4 * r) * t.K + k0;
; #pragma unroll
;     for (int j = 0; j < 4; ++j) { u32x4 o; o.x = cvt_pk_bf16(v[0][j] * g[0][0], v[1][j] * g[0][1]); o.y = cvt_pk_bf16(v[2][j] * g[0][2], v[3][j] * g[0][3]);
;         o.z = cvt_pk_bf16(v[4][j] * g[1][0], v[5][j] * g[1][1]); o.w = cvt_pk_bf16(v[6][j] * g[1][2], v[7][j] * g[1][3]); *(u32x4*)(dst + (size_t)j * t.K) = o; }
; }
.Ltwgo_3:
	s_lshr_b32 s36, s38, 5
	s_and_b32 s37, s38, 31
	s_lshl_b32 s40, s36, 18
	s_lshl_b32 s41, s37, 7
	s_add_u32 s40, s40, s41
	s_add_u32 s12, s12, s40
	s_addc_u32 s13, s13, 0
	global_load_dwordx4 v[0:3], v124, s[12:13]
	global_load_dwordx4 v[4:7], v125, s[12:13]
	global_load_dwordx4 v[8:11], v126, s[12:13]
	global_load_dwordx4 v[12:15], v127, s[12:13]
	global_load_dwordx4 v[16:19], v128, s[12:13]
	global_load_dwordx4 v[20:23], v129, s[12:13]
	global_load_dwordx4 v[24:27], v130, s[12:13]
	global_load_dwordx4 v[28:31], v131, s[12:13]
	s_and_b32 s40, s36, 15
	s_lshl_b32 s40, s40, 8
	v_add_u32_e32 v40, s40, v132
	global_load_dwordx4 v[32:35], v40, s[6:7]
	global_load_dwordx4 v[36:39], v40, s[6:7] offset:16
	s_waitcnt vmcnt(14)
	s_cmp_eq_u32 s49, 1
	s_cbranch_scc1 .Ltwg_4
	v_mov_b32_e32 v80, 1.0
	v_mov_b32_e32 v81, 1.0
	v_mov_b32_e32 v82, 1.0
	v_mov_b32_e32 v83, 1.0
	v_mov_b32_e32 v84, 1.0
	v_mov_b32_e32 v85, 1.0
	v_mov_b32_e32 v86, 1.0
	v_mov_b32_e32 v87, 1.0
.Ltwg_4:
	s_lshl_b32 s40, s51, 5
	v_lshl_add_u32 v88, v122, 2, s40
	v_mul_lo_u32 v88, v88, s48
	s_lshl_b32 s40, s50, 6
	v_lshl_add_u32 v89, v123, 3, s40
	v_add_lshl_u32 v88, v88, v89, 1
	s_lshl_b32 s40, s48, 1
	v_mul_f32_e32 v48, v48, v80
	v_mul_f32_e32 v49, v49, v80
	v_mul_f32_e32 v50, v50, v80
	v_mul_f32_e32 v51, v51, v80
	v_mul_f32_e32 v52, v52, v81
	v_mul_f32_e32 v53, v53, v81
	v_mul_f32_e32 v54, v54, v81
	v_mul_f32_e32 v55, v55, v81
	v_mul_f32_e32 v56, v56, v82
	v_mul_f32_e32 v57, v57, v82
	v_mul_f32_e32 v58, v58, v82
	v_mul_f32_e32 v59, v59, v82
	v_mul_f32_e32 v60, v60, v83
	v_mul_f32_e32 v61, v61, v83
	v_mul_f32_e32 v62, v62, v83
	v_mul_f32_e32 v63, v63, v83
	v_mul_f32_e32 v64, v64, v84
	v_mul_f32_e32 v65, v65, v84
	v_mul_f32_e32 v66, v66, v84
	v_mul_f32_e32 v67, v67, v84
	v_mul_f32_e32 v68, v68, v85
	v_mul_f32_e32 v69, v69, v85
	v_mul_f32_e32 v70, v70, v85
	v_mul_f32_e32 v71, v71, v85
	v_mul_f32_e32 v72, v72, v86
	v_mul_f32_e32 v73, v73, v86
	v_mul_f32_e32 v74, v74, v86
	v_mul_f32_e32 v75, v75, v86
	v_mul_f32_e32 v76, v76, v87
	v_mul_f32_e32 v77, v77, v87
	v_mul_f32_e32 v78, v78, v87
	v_mul_f32_e32 v79, v79, v87
	v_cvt_pk_bf16_f32 v80, v48, v52
	v_cvt_pk_bf16_f32 v81, v56, v60
	v_cvt_pk_bf16_f32 v82, v64, v68
	v_cvt_pk_bf16_f32 v83, v72, v76
	global_store_dwordx4 v88, v[80:83], s[46:47]
	v_add_u32_e32 v88, s40, v88
	v_cvt_pk_bf16_f32 v84, v49, v53
	v_cvt_pk_bf16_f32 v85, v57, v61
	v_cvt_pk_bf16_f32 v86, v65, v69
	v_cvt_pk_bf16_f32 v87, v73, v77
	global_store_dwordx4 v88, v[84:87], s[46:47]
	v_add_u32_e32 v88, s40, v88
	s_nop 1
	v_cvt_pk_bf16_f32 v80, v50, v54
	v_cvt_pk_bf16_f32 v81, v58, v62
	v_cvt_pk_bf16_f32 v82, v66, v70
	v_cvt_pk_bf16_f32 v83, v74, v78
	global_store_dwordx4 v88, v[80:83], s[46:47]
	v_add_u32_e32 v88, s40, v88
	v_cvt_pk_bf16_f32 v84, v51, v55
	v_cvt_pk_bf16_f32 v85, v59, v63
	v_cvt_pk_bf16_f32 v86, v67, v71
	v_cvt_pk_bf16_f32 v87, v75, v79
	global_store_dwordx4 v88, v[84:87], s[46:47]
	s_cmp_lt_u32 s3, 32
	s_cbranch_scc0 .Ltail_w3
	s_add_u32 s39, s3, 2016
	s_cmp_lt_u32 s39, 0x580
	s_cbranch_scc0 .Ltw5_5
	s_mov_b32 s38, s39
	s_mov_b32 s42, s4
	s_mov_b32 s43, s5
	s_add_u32 s46, s64, 0x1300000
	s_addc_u32 s47, s65, 0
	s_movk_i32 s48, 0xb00
	s_mov_b32 s49, 0
	s_branch .Ltwgo_5

; __device__ __forceinline__ unsigned cvt_pk_bf16(float lo, float hi) { unsigned r; asm volatile("v_cvt_pk_bf16_f32 %0, %1, %2" : "=v"(r) : "v"(lo), "v"(hi)); return r; }
; __device__ __forceinline__ void tr_load(const TrItem& t, int lane, f32x4 (&v)[8], f32x4 (&g)[2]) {
;     const int r = lane & 7, k0 = 64 * t.kb + 8 * (lane >> 3); const float* src = t.W + (size_t)k0 * t.ldw + t.sc0 + 4 * r;
; #pragma unroll
;     for (int i = 0; i < 8; ++i) v[i] = __builtin_nontemporal_load((const f32x4*)(src + (size_t)i * t.ldw));
;     if (t.gain) { g[0] = *(const f32x4*)(t.gain + k0); g[1] = *(const f32x4*)(t.gain + k0 + 4); } else { g[0] = (f32x4){1.f, 1.f, 1.f, 1.f}; g[1] = g[0]; }
; }
; __device__ __forceinline__ void tr_store(const TrItem& t, int lane, const f32x4 (&v)[8], const f32x4 (&g)[2]) {
;     const int r = lane & 7, k0 = 64 * t.kb + 8 * (lane >> 3); bf16_t* dst = t.WT + (size_t)(t.dr0 + 4 * r) * t.K + k0;
; #pragma unroll
;     for (int j = 0; j < 4; ++j) { u32x4 o; o.x = cvt_pk_bf16(v[0][j] * g[0][0], v[1][j] * g[0][1]); o.y = cvt_pk_bf16(v[2][j] * g[0][2], v[3][j] * g[0][3]);
;         o.z = cvt_pk_bf16(v[4][j] * g[1][0], v[5][j] * g[1][1]); o.w = cvt_pk_bf16(v[6][j] * g[1][2], v[7][j] * g[1][3]); *(u32x4*)(dst + (size_t)j * t.K) = o; }
; }
.Ltwgo_5:
	s_lshr_b32 s50, s38, 5
	s_and_b32 s51, s38, 31
	s_lshl_b32 s40, s50, 18
	s_lshl_b32 s41, s51, 7
	s_add_u32 s40, s40, s41
	s_add_u32 s42, s42, s40
	s_addc_u32 s43, s43, 0
	global_load_dwordx4 v[48:51], v124, s[42:43]
	global_load_dwordx4 v[52:55], v125, s[42:43]
	global_load_dwordx4 v[56:59], v126, s[42:43]
	global_load_dwordx4 v[60:63], v127, s[42:43]
	global_load_dwordx4 v[64:67], v128, s[42:43]
	global_load_dwordx4 v[68:71], v129, s[42:43]
	global_load_dwordx4 v[72:75], v130, s[42:43]
	global_load_dwordx4 v[76:79], v131, s[42:43]
	s_and_b32 s40, s50, 15
	s_lshl_b32 s40, s40, 8
	v_add_u32_e32 v88, s40, v132
	global_load_dwordx4 v[80:83], v88, s[6:7]
	global_load_dwordx4 v[84:87], v88, s[6:7] offset:16
	s_waitcnt vmcnt(14)
	s_cmp_eq_u32 s33, 1
	s_cbranch_scc1 .Ltwg_6
	v_mov_b32_e32 v32, 1.0
	v_mov_b32_e32 v33, 1.0
	v_mov_b32_e32 v34, 1.0
	v_mov_b32_e32 v35, 1.0
	v_mov_b32_e32 v36, 1.0
	v_mov_b32_e32 v37, 1.0
	v_mov_b32_e32 v38, 1.0
	v_mov_b32_e32 v39, 1.0
.Ltwg_6:
	s_lshl_b32 s40, s37, 5
	v_lshl_add_u32 v40, v122, 2, s40
	v_mul_lo_u32 v40, v40, s32
	s_lshl_b32 s40, s36, 6
	v_lshl_add_u32 v41, v123, 3, s40
	v_add_lshl_u32 v40, v40, v41, 1
	s_lshl_b32 s40, s32, 1
	v_mul_f32_e32 v0, v0, v32
	v_mul_f32_e32 v1, v1, v32
	v_mul_f32_e32 v2, v2, v32
	v_mul_f32_e32 v3, v3, v32
	v_mul_f32_e32 v4, v4, v33
	v_mul_f32_e32 v5, v5, v33
	v_mul_f32_e32 v6, v6, v33
	v_mul_f32_e32 v7, v7, v33
	v_mul_f32_e32 v8, v8, v34
	v_mul_f32_e32 v9, v9, v34
	v_mul_f32_e32 v10, v10, v34
	v_mul_f32_e32 v11, v11, v34
	v_mul_f32_e32 v12, v12, v35
	v_mul_f32_e32 v13, v13, v35
	v_mul_f32_e32 v14, v14, v35
	v_mul_f32_e32 v15, v15, v35
	v_mul_f32_e32 v16, v16, v36
	v_mul_f32_e32 v17, v17, v36
	v_mul_f32_e32 v18, v18, v36
	v_mul_f32_e32 v19, v19, v36
	v_mul_f32_e32 v20, v20, v37
	v_mul_f32_e32 v21, v21, v37
	v_mul_f32_e32 v22, v22, v37
	v_mul_f32_e32 v23, v23, v37
	v_mul_f32_e32 v24, v24, v38
	v_mul_f32_e32 v25, v25, v38
	v_mul_f32_e32 v26, v26, v38
	v_mul_f32_e32 v27, v27, v38
	v_mul_f32_e32 v28, v28, v39
	v_mul_f32_e32 v29, v29, v39
	v_mul_f32_e32 v30, v30, v39
	v_mul_f32_e32 v31, v31, v39
	v_cvt_pk_bf16_f32 v32, v0, v4
	v_cvt_pk_bf16_f32 v33, v8, v12
	v_cvt_pk_bf16_f32 v34, v16, v20
	v_cvt_pk_bf16_f32 v35, v24, v28
	global_store_dwordx4 v40, v[32:35], s[14:15]
	v_add_u32_e32 v40, s40, v40
	v_cvt_pk_bf16_f32 v36, v1, v5
	v_cvt_pk_bf16_f32 v37, v9, v13
	v_cvt_pk_bf16_f32 v38, v17, v21
	v_cvt_pk_bf16_f32 v39, v25, v29
	global_store_dwordx4 v40, v[36:39], s[14:15]
	v_add_u32_e32 v40, s40, v40
	s_nop 1
	v_cvt_pk_bf16_f32 v32, v2, v6
	v_cvt_pk_bf16_f32 v33, v10, v14
	v_cvt_pk_bf16_f32 v34, v18, v22
	v_cvt_pk_bf16_f32 v35, v26, v30
	global_store_dwordx4 v40, v[32:35], s[14:15]
	v_add_u32_e32 v40, s40, v40
	v_cvt_pk_bf16_f32 v36, v3, v7
	v_cvt_pk_bf16_f32 v37, v11, v15
	v_cvt_pk_bf16_f32 v38, v19, v23
	v_cvt_pk_bf16_f32 v39, v27, v31
	global_store_dwordx4 v40, v[36:39], s[14:15]
	s_waitcnt vmcnt(4)
	s_cmp_eq_u32 s49, 1
	s_cbranch_scc1 .Ltwg_7
	v_mov_b32_e32 v80, 1.0
	v_mov_b32_e32 v81, 1.0
	v_mov_b32_e32 v82, 1.0
	v_mov_b32_e32 v83, 1.0
	v_mov_b32_e32 v84, 1.0
	v_mov_b32_e32 v85, 1.0
	v_mov_b32_e32 v86, 1.0
	v_mov_b32_e32 v87, 1.0
.Ltwg_7:
	s_lshl_b32 s40, s51, 5
	v_lshl_add_u32 v88, v122, 2, s40
	v_mul_lo_u32 v88, v88, s48
	s_lshl_b32 s40, s50, 6
	v_lshl_add_u32 v89, v123, 3, s40
	v_add_lshl_u32 v88, v88, v89, 1
	s_lshl_b32 s40, s48, 1
	v_mul_f32_e32 v48, v48, v80
	v_mul_f32_e32 v49, v49, v80
	v_mul_f32_e32 v50, v50, v80
	v_mul_f32_e32 v51, v51, v80
	v_mul_f32_e32 v52, v52, v81
	v_mul_f32_e32 v53, v53, v81
	v_mul_f32_e32 v54, v54, v81
	v_mul_f32_e32 v55, v55, v81
	v_mul_f32_e32 v56, v56, v82
	v_mul_f32_e32 v57, v57, v82
	v_mul_f32_e32 v58, v58, v82
	v_mul_f32_e32 v59, v59, v82
	v_mul_f32_e32 v60, v60, v83
	v_mul_f32_e32 v61, v61, v83
	v_mul_f32_e32 v62, v62, v83
	v_mul_f32_e32 v63, v63, v83
	v_mul_f32_e32 v64, v64, v84
	v_mul_f32_e32 v65, v65, v84
	v_mul_f32_e32 v66, v66, v84
	v_mul_f32_e32 v67, v67, v84
	v_mul_f32_e32 v68, v68, v85
	v_mul_f32_e32 v69, v69, v85
	v_mul_f32_e32 v70, v70, v85
	v_mul_f32_e32 v71, v71, v85
	v_mul_f32_e32 v72, v72, v86
	v_mul_f32_e32 v73, v73, v86
	v_mul_f32_e32 v74, v74, v86
	v_mul_f32_e32 v75, v75, v86
	v_mul_f32_e32 v76, v76, v87
	v_mul_f32_e32 v77, v77, v87
	v_mul_f32_e32 v78, v78, v87
	v_mul_f32_e32 v79, v79, v87
	v_cvt_pk_bf16_f32 v80, v48, v52
	v_cvt_pk_bf16_f32 v81, v56, v60
	v_cvt_pk_bf16_f32 v82, v64, v68
	v_cvt_pk_bf16_f32 v83, v72, v76
	global_store_dwordx4 v88, v[80:83], s[46:47]
	v_add_u32_e32 v88, s40, v88
	v_cvt_pk_bf16_f32 v84, v49, v53
	v_cvt_pk_bf16_f32 v85, v57, v61
	v_cvt_pk_bf16_f32 v86, v65, v69
	v_cvt_pk_bf16_f32 v87, v73, v77
	global_store_dwordx4 v88, v[84:87], s[46:47]
	v_add_u32_e32 v88, s40, v88
	s_nop 1
	v_cvt_pk_bf16_f32 v80, v50, v54
	v_cvt_pk_bf16_f32 v81, v58, v62
	v_cvt_pk_bf16_f32 v82, v66, v70
	v_cvt_pk_bf16_f32 v83, v74, v78
	global_store_dwordx4 v88, v[80:83], s[46:47]
	v_add_u32_e32 v88, s40, v88
	v_cvt_pk_bf16_f32 v84, v51, v55
	v_cvt_pk_bf16_f32 v85, v59, v63
	v_cvt_pk_bf16_f32 v86, v67, v71
	v_cvt_pk_bf16_f32 v87, v75, v79
	global_store_dwordx4 v88, v[84:87], s[46:47]
	s_branch .Ltail_w_done
.Ltail_w3:
	s_waitcnt vmcnt(4)
	s_cmp_eq_u32 s33, 1
	s_cbranch_scc1 .Ltwg_8
	v_mov_b32_e32 v32, 1.0
	v_mov_b32_e32 v33, 1.0
	v_mov_b32_e32 v34, 1.0
	v_mov_b32_e32 v35, 1.0
	v_mov_b32_e32 v36, 1.0
	v_mov_b32_e32 v37, 1.0
	v_mov_b32_e32 v38, 1.0
	v_mov_b32_e32 v39, 1.0
; __device__ __forceinline__ unsigned cvt_pk_bf16(float lo, float hi) { unsigned r; asm volatile("v_cvt_pk_bf16_f32 %0, %1, %2" : "=v"(r) : "v"(lo), "v"(hi)); return r; }
; __device__ __forceinline__ void tr_store(const TrItem& t, int lane, const f32x4 (&v)[8], const f32x4 (&g)[2]) {
;     const int r = lane & 7, k0 = 64 * t.kb + 8 * (lane >> 3); bf16_t* dst = t.WT + (size_t)(t.dr0 + 4 * r) * t.K + k0;
; #pragma unroll
;     for (int j = 0; j < 4; ++j) { u32x4 o; o.x = cvt_pk_bf16(v[0][j] * g[0][0], v[1][j] * g[0][1]); o.y = cvt_pk_bf16(v[2][j] * g[0][2], v[3][j] * g[0][3]);
;         o.z = cvt_pk_bf16(v[4][j] * g[1][0], v[5][j] * g[1][1]); o.w = cvt_pk_bf16(v[6][j] * g[1][2], v[7][j] * g[1][3]); *(u32x4*)(dst + (size_t)j * t.K) = o; }
; }
; __device__ __forceinline__ void p0_prologue(const Params& p, unsigned char* lds) {
;     ...
;     { float* scs = p.out + O_SCS; const float* sc = p.in[I_SC]; constexpr int RW = (CW - 1 - DS) * MIXB / 4; constexpr size_t NCP = (size_t)DB * RW;
;       for (size_t i0 = gt; i0 < NCP; i0 += 4 * NT) { f32x4 v[4]; size_t d[4];
; #pragma unroll
;           for (int q = 0; q < 4; ++q) { const size_t i = i0 + q * NT < NCP ? i0 + q * NT : i0, n = i / RW, w = i % RW; d[q] = n * (CW - 1) * MIXB + w * 4; v[q] = __builtin_nontemporal_load((const f32x4*)(sc + d[q] + DS * MIXB)); }
; #pragma unroll
;           for (int q = 0; q < 4; ++q) __builtin_nontemporal_store(v[q], (f32x4*)(scs + d[q])); } }
.Ltwg_8:
	s_lshl_b32 s40, s37, 5
	v_lshl_add_u32 v40, v122, 2, s40
	v_mul_lo_u32 v40, v40, s32
	s_lshl_b32 s40, s36, 6
	v_lshl_add_u32 v41, v123, 3, s40
	v_add_lshl_u32 v40, v40, v41, 1
	s_lshl_b32 s40, s32, 1
	v_mul_f32_e32 v0, v0, v32
	v_mul_f32_e32 v1, v1, v32
	v_mul_f32_e32 v2, v2, v32
	v_mul_f32_e32 v3, v3, v32
	v_mul_f32_e32 v4, v4, v33
	v_mul_f32_e32 v5, v5, v33
	v_mul_f32_e32 v6, v6, v33
	v_mul_f32_e32 v7, v7, v33
	v_mul_f32_e32 v8, v8, v34
	v_mul_f32_e32 v9, v9, v34
	v_mul_f32_e32 v10, v10, v34
	v_mul_f32_e32 v11, v11, v34
	v_mul_f32_e32 v12, v12, v35
	v_mul_f32_e32 v13, v13, v35
	v_mul_f32_e32 v14, v14, v35
	v_mul_f32_e32 v15, v15, v35
	v_mul_f32_e32 v16, v16, v36
	v_mul_f32_e32 v17, v17, v36
	v_mul_f32_e32 v18, v18, v36
	v_mul_f32_e32 v19, v19, v36
	v_mul_f32_e32 v20, v20, v37
	v_mul_f32_e32 v21, v21, v37
	v_mul_f32_e32 v22, v22, v37
	v_mul_f32_e32 v23, v23, v37
	v_mul_f32_e32 v24, v24, v38
	v_mul_f32_e32 v25, v25, v38
	v_mul_f32_e32 v26, v26, v38
	v_mul_f32_e32 v27, v27, v38
	v_mul_f32_e32 v28, v28, v39
	v_mul_f32_e32 v29, v29, v39
	v_mul_f32_e32 v30, v30, v39
	v_mul_f32_e32 v31, v31, v39
	v_cvt_pk_bf16_f32 v32, v0, v4
	v_cvt_pk_bf16_f32 v33, v8, v12
	v_cvt_pk_bf16_f32 v34, v16, v20
	v_cvt_pk_bf16_f32 v35, v24, v28
	global_store_dwordx4 v40, v[32:35], s[14:15]
	v_add_u32_e32 v40, s40, v40
	v_cvt_pk_bf16_f32 v36, v1, v5
	v_cvt_pk_bf16_f32 v37, v9, v13
	v_cvt_pk_bf16_f32 v38, v17, v21
	v_cvt_pk_bf16_f32 v39, v25, v29
	global_store_dwordx4 v40, v[36:39], s[14:15]
	v_add_u32_e32 v40, s40, v40
	s_nop 1
	v_cvt_pk_bf16_f32 v32, v2, v6
	v_cvt_pk_bf16_f32 v33, v10, v14
	v_cvt_pk_bf16_f32 v34, v18, v22
	v_cvt_pk_bf16_f32 v35, v26, v30
	global_store_dwordx4 v40, v[32:35], s[14:15]
	v_add_u32_e32 v40, s40, v40
	v_cvt_pk_bf16_f32 v36, v3, v7
	v_cvt_pk_bf16_f32 v37, v11, v15
	v_cvt_pk_bf16_f32 v38, v19, v23
	v_cvt_pk_bf16_f32 v39, v27, v31
	global_store_dwordx4 v40, v[36:39], s[14:15]
.Ltail_w_done:
	v_readlane_b32 s4, v247, 10
	v_readlane_b32 s5, v247, 11
	v_readlane_b32 s6, v247, 30
	v_readlane_b32 s7, v247, 31
	s_add_u32 s6, s6, 0x6478000
	s_addc_u32 s7, s7, 0
	s_add_u32 s4, s4, 0x2000
	s_addc_u32 s5, s5, 0
	s_mul_i32 s10, s3, 9
	s_min_u32 s11, s3, 0x260
	s_add_u32 s10, s10, s11
	s_cmp_lt_u32 s3, 0x260
	s_cbranch_scc0 .Ltail_scs9
	s_add_u32 s39, s10, 0
	s_mul_hi_u32 s38, s39, 0x4ec4ec4f
	s_lshr_b32 s38, s38, 4
	s_mul_i32 s40, s38, 52
	s_sub_u32 s40, s39, s40
	s_mul_i32 s38, s38, 0xf000
	s_lshl_b32 s40, s40, 10
	s_add_u32 s38, s38, s40
	s_add_u32 s12, s4, s38
	s_addc_u32 s13, s5, 0
	global_load_dwordx4 v[0:3], v121, s[12:13] nt
	s_add_u32 s39, s10, 1
	s_mul_hi_u32 s38, s39, 0x4ec4ec4f
	s_lshr_b32 s38, s38, 4
	s_mul_i32 s40, s38, 52
	s_sub_u32 s40, s39, s40
	s_mul_i32 s38, s38, 0xf000
	s_lshl_b32 s40, s40, 10
	s_add_u32 s38, s38, s40
	s_add_u32 s12, s4, s38
	s_addc_u32 s13, s5, 0
	global_load_dwordx4 v[4:7], v121, s[12:13] nt
	s_add_u32 s39, s10, 2
	s_mul_hi_u32 s38, s39, 0x4ec4ec4f
	s_lshr_b32 s38, s38, 4
	s_mul_i32 s40, s38, 52
	s_sub_u32 s40, s39, s40
	s_mul_i32 s38, s38, 0xf000
	s_lshl_b32 s40, s40, 10
	s_add_u32 s38, s38, s40
	s_add_u32 s12, s4, s38
	s_addc_u32 s13, s5, 0
	global_load_dwordx4 v[8:11], v121, s[12:13] nt
	s_add_u32 s39, s10, 3
	s_mul_hi_u32 s38, s39, 0x4ec4ec4f
	s_lshr_b32 s38, s38, 4
	s_mul_i32 s40, s38, 52
	s_sub_u32 s40, s39, s40
	s_mul_i32 s38, s38, 0xf000
	s_lshl_b32 s40, s40, 10
	s_add_u32 s38, s38, s40
	s_add_u32 s12, s4, s38
	s_addc_u32 s13, s5, 0
	global_load_dwordx4 v[12:15], v121, s[12:13] nt
	s_add_u32 s39, s10, 4
	s_mul_hi_u32 s38, s39, 0x4ec4ec4f
	s_lshr_b32 s38, s38, 4
	s_mul_i32 s40, s38, 52
	s_sub_u32 s40, s39, s40
	s_mul_i32 s38, s38, 0xf000
	s_lshl_b32 s40, s40, 10
	s_add_u32 s38, s38, s40
	s_add_u32 s12, s4, s38
	s_addc_u32 s13, s5, 0
	global_load_dwordx4 v[16:19], v121, s[12:13] nt
	s_add_u32 s39, s10, 5
	s_mul_hi_u32 s38, s39, 0x4ec4ec4f
	s_lshr_b32 s38, s38, 4
	s_mul_i32 s40, s38, 52
	s_sub_u32 s40, s39, s40
	s_mul_i32 s38, s38, 0xf000
	s_lshl_b32 s40, s40, 10
	s_add_u32 s38, s38, s40
	s_add_u32 s12, s4, s38
	s_addc_u32 s13, s5, 0
	global_load_dwordx4 v[20:23], v121, s[12:13] nt
	s_add_u32 s39, s10, 6
	s_mul_hi_u32 s38, s39, 0x4ec4ec4f
	s_lshr_b32 s38, s38, 4
	s_mul_i32 s40, s38, 52
	s_sub_u32 s40, s39, s40
	s_mul_i32 s38, s38, 0xf000
	s_lshl_b32 s40, s40, 10
	s_add_u32 s38, s38, s40
	s_add_u32 s12, s4, s38
	s_addc_u32 s13, s5, 0
	global_load_dwordx4 v[24:27], v121, s[12:13] nt
	s_add_u32 s39, s10, 7
	s_mul_hi_u32 s38, s39, 0x4ec4ec4f
	s_lshr_b32 s38, s38, 4
	s_mul_i32 s40, s38, 52
	s_sub_u32 s40, s39, s40
	s_mul_i32 s38, s38, 0xf000
	s_lshl_b32 s40, s40, 10
	s_add_u32 s38, s38, s40
	s_add_u32 s12, s4, s38
	s_addc_u32 s13, s5, 0
	global_load_dwordx4 v[28:31], v121, s[12:13] nt
	s_add_u32 s39, s10, 8
	s_mul_hi_u32 s38, s39, 0x4ec4ec4f
	s_lshr_b32 s38, s38, 4
	s_mul_i32 s40, s38, 52
	s_sub_u32 s40, s39, s40
	s_mul_i32 s38, s38, 0xf000
	s_lshl_b32 s40, s40, 10
	s_add_u32 s38, s38, s40
	s_add_u32 s12, s4, s38
	s_addc_u32 s13, s5, 0
	global_load_dwordx4 v[32:35], v121, s[12:13] nt
	s_add_u32 s39, s10, 9
	s_mul_hi_u32 s38, s39, 0x4ec4ec4f
	s_lshr_b32 s38, s38, 4
	s_mul_i32 s40, s38, 52
	s_sub_u32 s40, s39, s40
	s_mul_i32 s38, s38, 0xf000
	s_lshl_b32 s40, s40, 10
	s_add_u32 s38, s38, s40
	s_add_u32 s12, s4, s38
	s_addc_u32 s13, s5, 0
	global_load_dwordx4 v[36:39], v121, s[12:13] nt
	s_add_u32 s39, s10, 0
	s_mul_hi_u32 s38, s39, 0x4ec4ec4f
	s_lshr_b32 s38, s38, 4
	s_mul_i32 s40, s38, 52
	s_sub_u32 s40, s39, s40
	s_mul_i32 s38, s38, 0xf000
	s_lshl_b32 s40, s40, 10
	s_add_u32 s38, s38, s40
	s_add_u32 s14, s6, s38
	s_addc_u32 s15, s7, 0
	s_waitcnt vmcnt(9)
; __device__ __forceinline__ void p0_prologue(const Params& p, unsigned char* lds) {
;     ...
;     { float* scs = p.out + O_SCS; const float* sc = p.in[I_SC]; constexpr int RW = (CW - 1 - DS) * MIXB / 4; constexpr size_t NCP = (size_t)DB * RW;
;       for (size_t i0 = gt; i0 < NCP; i0 += 4 * NT) { f32x4 v[4]; size_t d[4];
; #pragma unroll
;           for (int q = 0; q < 4; ++q) { const size_t i = i0 + q * NT < NCP ? i0 + q * NT : i0, n = i / RW, w = i % RW; d[q] = n * (CW - 1) * MIXB + w * 4; v[q] = __builtin_nontemporal_load((const f32x4*)(sc + d[q] + DS * MIXB)); }
; #pragma unroll
;           for (int q = 0; q < 4; ++q) __builtin_nontemporal_store(v[q], (f32x4*)(scs + d[q])); } }
	global_store_dwordx4 v121, v[0:3], s[14:15] nt
	s_add_u32 s39, s10, 1
	s_mul_hi_u32 s38, s39, 0x4ec4ec4f
	s_lshr_b32 s38, s38, 4
	s_mul_i32 s40, s38, 52
	s_sub_u32 s40, s39, s40
	s_mul_i32 s38, s38, 0xf000
	s_lshl_b32 s40, s40, 10
	s_add_u32 s38, s38, s40
	s_add_u32 s14, s6, s38
	s_addc_u32 s15, s7, 0
	s_waitcnt vmcnt(9)
	global_store_dwordx4 v121, v[4:7], s[14:15] nt
	s_add_u32 s39, s10, 2
	s_mul_hi_u32 s38, s39, 0x4ec4ec4f
	s_lshr_b32 s38, s38, 4
	s_mul_i32 s40, s38, 52
	s_sub_u32 s40, s39, s40
	s_mul_i32 s38, s38, 0xf000
	s_lshl_b32 s40, s40, 10
	s_add_u32 s38, s38, s40
	s_add_u32 s14, s6, s38
	s_addc_u32 s15, s7, 0
	s_waitcnt vmcnt(9)
	global_store_dwordx4 v121, v[8:11], s[14:15] nt
	s_add_u32 s39, s10, 3
	s_mul_hi_u32 s38, s39, 0x4ec4ec4f
	s_lshr_b32 s38, s38, 4
	s_mul_i32 s40, s38, 52
	s_sub_u32 s40, s39, s40
	s_mul_i32 s38, s38, 0xf000
	s_lshl_b32 s40, s40, 10
	s_add_u32 s38, s38, s40
	s_add_u32 s14, s6, s38
	s_addc_u32 s15, s7, 0
	s_waitcnt vmcnt(9)
	global_store_dwordx4 v121, v[12:15], s[14:15] nt
	s_add_u32 s39, s10, 4
	s_mul_hi_u32 s38, s39, 0x4ec4ec4f
	s_lshr_b32 s38, s38, 4
	s_mul_i32 s40, s38, 52
	s_sub_u32 s40, s39, s40
	s_mul_i32 s38, s38, 0xf000
	s_lshl_b32 s40, s40, 10
	s_add_u32 s38, s38, s40
	s_add_u32 s14, s6, s38
	s_addc_u32 s15, s7, 0
	s_waitcnt vmcnt(9)
	global_store_dwordx4 v121, v[16:19], s[14:15] nt
	s_add_u32 s39, s10, 5
	s_mul_hi_u32 s38, s39, 0x4ec4ec4f
	s_lshr_b32 s38, s38, 4
	s_mul_i32 s40, s38, 52
	s_sub_u32 s40, s39, s40
	s_mul_i32 s38, s38, 0xf000
	s_lshl_b32 s40, s40, 10
	s_add_u32 s38, s38, s40
	s_add_u32 s14, s6, s38
	s_addc_u32 s15, s7, 0
	s_waitcnt vmcnt(9)
	global_store_dwordx4 v121, v[20:23], s[14:15] nt
	s_add_u32 s39, s10, 6
	s_mul_hi_u32 s38, s39, 0x4ec4ec4f
	s_lshr_b32 s38, s38, 4
	s_mul_i32 s40, s38, 52
	s_sub_u32 s40, s39, s40
	s_mul_i32 s38, s38, 0xf000
	s_lshl_b32 s40, s40, 10
	s_add_u32 s38, s38, s40
	s_add_u32 s14, s6, s38
	s_addc_u32 s15, s7, 0
	s_waitcnt vmcnt(9)
	global_store_dwordx4 v121, v[24:27], s[14:15] nt
	s_add_u32 s39, s10, 7
	s_mul_hi_u32 s38, s39, 0x4ec4ec4f
	s_lshr_b32 s38, s38, 4
	s_mul_i32 s40, s38, 52
	s_sub_u32 s40, s39, s40
	s_mul_i32 s38, s38, 0xf000
	s_lshl_b32 s40, s40, 10
	s_add_u32 s38, s38, s40
	s_add_u32 s14, s6, s38
	s_addc_u32 s15, s7, 0
	s_waitcnt vmcnt(9)
	global_store_dwordx4 v121, v[28:31], s[14:15] nt
	s_add_u32 s39, s10, 8
	s_mul_hi_u32 s38, s39, 0x4ec4ec4f
	s_lshr_b32 s38, s38, 4
	s_mul_i32 s40, s38, 52
	s_sub_u32 s40, s39, s40
	s_mul_i32 s38, s38, 0xf000
	s_lshl_b32 s40, s40, 10
	s_add_u32 s38, s38, s40
	s_add_u32 s14, s6, s38
	s_addc_u32 s15, s7, 0
	s_waitcnt vmcnt(9)
	global_store_dwordx4 v121, v[32:35], s[14:15] nt
	s_add_u32 s39, s10, 9
	s_mul_hi_u32 s38, s39, 0x4ec4ec4f
	s_lshr_b32 s38, s38, 4
	s_mul_i32 s40, s38, 52
	s_sub_u32 s40, s39, s40
	s_mul_i32 s38, s38, 0xf000
	s_lshl_b32 s40, s40, 10
	s_add_u32 s38, s38, s40
	s_add_u32 s14, s6, s38
	s_addc_u32 s15, s7, 0
	s_waitcnt vmcnt(9)
	global_store_dwordx4 v121, v[36:39], s[14:15] nt
	s_branch .Ltail_done
; __device__ __forceinline__ void p0_prologue(const Params& p, unsigned char* lds) {
;     ...
;     { float* scs = p.out + O_SCS; const float* sc = p.in[I_SC]; constexpr int RW = (CW - 1 - DS) * MIXB / 4; constexpr size_t NCP = (size_t)DB * RW;
;       for (size_t i0 = gt; i0 < NCP; i0 += 4 * NT) { f32x4 v[4]; size_t d[4];
; #pragma unroll
;           for (int q = 0; q < 4; ++q) { const size_t i = i0 + q * NT < NCP ? i0 + q * NT : i0, n = i / RW, w = i % RW; d[q] = n * (CW - 1) * MIXB + w * 4; v[q] = __builtin_nontemporal_load((const f32x4*)(sc + d[q] + DS * MIXB)); }
; #pragma unroll
;           for (int q = 0; q < 4; ++q) __builtin_nontemporal_store(v[q], (f32x4*)(scs + d[q])); } }
.Ltail_scs9:
	s_add_u32 s39, s10, 0
	s_mul_hi_u32 s38, s39, 0x4ec4ec4f
	s_lshr_b32 s38, s38, 4
	s_mul_i32 s40, s38, 52
	s_sub_u32 s40, s39, s40
	s_mul_i32 s38, s38, 0xf000
	s_lshl_b32 s40, s40, 10
	s_add_u32 s38, s38, s40
	s_add_u32 s12, s4, s38
	s_addc_u32 s13, s5, 0
	global_load_dwordx4 v[0:3], v121, s[12:13] nt
	s_add_u32 s39, s10, 1
	s_mul_hi_u32 s38, s39, 0x4ec4ec4f
	s_lshr_b32 s38, s38, 4
	s_mul_i32 s40, s38, 52
	s_sub_u32 s40, s39, s40
	s_mul_i32 s38, s38, 0xf000
	s_lshl_b32 s40, s40, 10
	s_add_u32 s38, s38, s40
	s_add_u32 s12, s4, s38
	s_addc_u32 s13, s5, 0
	global_load_dwordx4 v[4:7], v121, s[12:13] nt
	s_add_u32 s39, s10, 2
	s_mul_hi_u32 s38, s39, 0x4ec4ec4f
	s_lshr_b32 s38, s38, 4
	s_mul_i32 s40, s38, 52
	s_sub_u32 s40, s39, s40
	s_mul_i32 s38, s38, 0xf000
	s_lshl_b32 s40, s40, 10
	s_add_u32 s38, s38, s40
	s_add_u32 s12, s4, s38
	s_addc_u32 s13, s5, 0
	global_load_dwordx4 v[8:11], v121, s[12:13] nt
	s_add_u32 s39, s10, 3
	s_mul_hi_u32 s38, s39, 0x4ec4ec4f
	s_lshr_b32 s38, s38, 4
	s_mul_i32 s40, s38, 52
	s_sub_u32 s40, s39, s40
	s_mul_i32 s38, s38, 0xf000
	s_lshl_b32 s40, s40, 10
	s_add_u32 s38, s38, s40
	s_add_u32 s12, s4, s38
	s_addc_u32 s13, s5, 0
	global_load_dwordx4 v[12:15], v121, s[12:13] nt
	s_add_u32 s39, s10, 4
	s_mul_hi_u32 s38, s39, 0x4ec4ec4f
	s_lshr_b32 s38, s38, 4
	s_mul_i32 s40, s38, 52
	s_sub_u32 s40, s39, s40
	s_mul_i32 s38, s38, 0xf000
	s_lshl_b32 s40, s40, 10
	s_add_u32 s38, s38, s40
	s_add_u32 s12, s4, s38
	s_addc_u32 s13, s5, 0
	global_load_dwordx4 v[16:19], v121, s[12:13] nt
	s_add_u32 s39, s10, 5
	s_mul_hi_u32 s38, s39, 0x4ec4ec4f
	s_lshr_b32 s38, s38, 4
	s_mul_i32 s40, s38, 52
	s_sub_u32 s40, s39, s40
	s_mul_i32 s38, s38, 0xf000
	s_lshl_b32 s40, s40, 10
	s_add_u32 s38, s38, s40
	s_add_u32 s12, s4, s38
	s_addc_u32 s13, s5, 0
	global_load_dwordx4 v[20:23], v121, s[12:13] nt
	s_add_u32 s39, s10, 6
	s_mul_hi_u32 s38, s39, 0x4ec4ec4f
	s_lshr_b32 s38, s38, 4
	s_mul_i32 s40, s38, 52
	s_sub_u32 s40, s39, s40
	s_mul_i32 s38, s38, 0xf000
	s_lshl_b32 s40, s40, 10
	s_add_u32 s38, s38, s40
	s_add_u32 s12, s4, s38
	s_addc_u32 s13, s5, 0
	global_load_dwordx4 v[24:27], v121, s[12:13] nt
	s_add_u32 s39, s10, 7
	s_mul_hi_u32 s38, s39, 0x4ec4ec4f
	s_lshr_b32 s38, s38, 4
	s_mul_i32 s40, s38, 52
	s_sub_u32 s40, s39, s40
	s_mul_i32 s38, s38, 0xf000
	s_lshl_b32 s40, s40, 10
	s_add_u32 s38, s38, s40
	s_add_u32 s12, s4, s38
	s_addc_u32 s13, s5, 0
	global_load_dwordx4 v[28:31], v121, s[12:13] nt
	s_add_u32 s39, s10, 8
	s_mul_hi_u32 s38, s39, 0x4ec4ec4f
	s_lshr_b32 s38, s38, 4
	s_mul_i32 s40, s38, 52
	s_sub_u32 s40, s39, s40
	s_mul_i32 s38, s38, 0xf000
	s_lshl_b32 s40, s40, 10
	s_add_u32 s38, s38, s40
	s_add_u32 s12, s4, s38
	s_addc_u32 s13, s5, 0
	global_load_dwordx4 v[32:35], v121, s[12:13] nt
	s_add_u32 s39, s10, 0
	s_mul_hi_u32 s38, s39, 0x4ec4ec4f
	s_lshr_b32 s38, s38, 4
	s_mul_i32 s40, s38, 52
	s_sub_u32 s40, s39, s40
	s_mul_i32 s38, s38, 0xf000
	s_lshl_b32 s40, s40, 10
	s_add_u32 s38, s38, s40
	s_add_u32 s14, s6, s38
	s_addc_u32 s15, s7, 0
	s_waitcnt vmcnt(8)
	global_store_dwordx4 v121, v[0:3], s[14:15] nt
	s_add_u32 s39, s10, 1
	s_mul_hi_u32 s38, s39, 0x4ec4ec4f
	s_lshr_b32 s38, s38, 4
	s_mul_i32 s40, s38, 52
	s_sub_u32 s40, s39, s40
	s_mul_i32 s38, s38, 0xf000
	s_lshl_b32 s40, s40, 10
	s_add_u32 s38, s38, s40
	s_add_u32 s14, s6, s38
	s_addc_u32 s15, s7, 0
	s_waitcnt vmcnt(8)
	global_store_dwordx4 v121, v[4:7], s[14:15] nt
	s_add_u32 s39, s10, 2
	s_mul_hi_u32 s38, s39, 0x4ec4ec4f
	s_lshr_b32 s38, s38, 4
	s_mul_i32 s40, s38, 52
	s_sub_u32 s40, s39, s40
	s_mul_i32 s38, s38, 0xf000
	s_lshl_b32 s40, s40, 10
	s_add_u32 s38, s38, s40
	s_add_u32 s14, s6, s38
	s_addc_u32 s15, s7, 0
	s_waitcnt vmcnt(8)
	global_store_dwordx4 v121, v[8:11], s[14:15] nt
	s_add_u32 s39, s10, 3
	s_mul_hi_u32 s38, s39, 0x4ec4ec4f
	s_lshr_b32 s38, s38, 4
	s_mul_i32 s40, s38, 52
	s_sub_u32 s40, s39, s40
	s_mul_i32 s38, s38, 0xf000
	s_lshl_b32 s40, s40, 10
	s_add_u32 s38, s38, s40
	s_add_u32 s14, s6, s38
	s_addc_u32 s15, s7, 0
	s_waitcnt vmcnt(8)
	global_store_dwordx4 v121, v[12:15], s[14:15] nt
	s_add_u32 s39, s10, 4
	s_mul_hi_u32 s38, s39, 0x4ec4ec4f
	s_lshr_b32 s38, s38, 4
	s_mul_i32 s40, s38, 52
	s_sub_u32 s40, s39, s40
	s_mul_i32 s38, s38, 0xf000
	s_lshl_b32 s40, s40, 10
	s_add_u32 s38, s38, s40
	s_add_u32 s14, s6, s38
	s_addc_u32 s15, s7, 0
	s_waitcnt vmcnt(8)
	global_store_dwordx4 v121, v[16:19], s[14:15] nt
	s_add_u32 s39, s10, 5
	s_mul_hi_u32 s38, s39, 0x4ec4ec4f
	s_lshr_b32 s38, s38, 4
	s_mul_i32 s40, s38, 52
	s_sub_u32 s40, s39, s40
	s_mul_i32 s38, s38, 0xf000
	s_lshl_b32 s40, s40, 10
	s_add_u32 s38, s38, s40
	s_add_u32 s14, s6, s38
	s_addc_u32 s15, s7, 0
	s_waitcnt vmcnt(8)
	global_store_dwordx4 v121, v[20:23], s[14:15] nt
	s_add_u32 s39, s10, 6
	s_mul_hi_u32 s38, s39, 0x4ec4ec4f
	s_lshr_b32 s38, s38, 4
	s_mul_i32 s40, s38, 52
	s_sub_u32 s40, s39, s40
	s_mul_i32 s38, s38, 0xf000
	s_lshl_b32 s40, s40, 10
	s_add_u32 s38, s38, s40
	s_add_u32 s14, s6, s38
	s_addc_u32 s15, s7, 0
	s_waitcnt vmcnt(8)
	global_store_dwordx4 v121, v[24:27], s[14:15] nt
	s_add_u32 s39, s10, 7
	s_mul_hi_u32 s38, s39, 0x4ec4ec4f
	s_lshr_b32 s38, s38, 4
	s_mul_i32 s40, s38, 52
	s_sub_u32 s40, s39, s40
	s_mul_i32 s38, s38, 0xf000
	s_lshl_b32 s40, s40, 10
	s_add_u32 s38, s38, s40
	s_add_u32 s14, s6, s38
	s_addc_u32 s15, s7, 0
	s_waitcnt vmcnt(8)
	global_store_dwordx4 v121, v[28:31], s[14:15] nt
	s_add_u32 s39, s10, 8
	s_mul_hi_u32 s38, s39, 0x4ec4ec4f
	s_lshr_b32 s38, s38, 4
	s_mul_i32 s40, s38, 52
	s_sub_u32 s40, s39, s40
	s_mul_i32 s38, s38, 0xf000
	s_lshl_b32 s40, s40, 10
	s_add_u32 s38, s38, s40
	s_add_u32 s14, s6, s38
	s_addc_u32 s15, s7, 0
	s_waitcnt vmcnt(8)
	global_store_dwordx4 v121, v[32:35], s[14:15] nt
